# attention kv loop (latency-chain bound): K-fragment LDS reads issued before the next tile's global loads; P.V k-step-0 MFMAs issued after the first 8 probabilities so the second 8 exponentials overlap
# baseline (speedup 1.0000x reference)
; #define MFMA(a, b, c) __builtin_amdgcn_mfma_f32_32x32x16_bf16((a), (b), (c), 0, 0, 0)
; DI void phase4(const Params& p, char* smem) {
;     ...
;       for (int kt = 0; kt <= c; ++kt) {
;         __syncthreads();
; #pragma unroll
;         for (int i = 0; i < 6; ++i) *(u32x4*)(ksw + i * 32) = kr[i];
; #pragma unroll
;         for (int i = 0; i < 4; ++i) { u32x2 lo2 = {vr[i][0], vr[i][1]}, hi2 = {vr[i][2], vr[i][3]}; *(u32x2*)(vsw + i * 16) = lo2; *(u32x2*)(vsw + i * 16 + 4) = hi2; }
;         __syncthreads();
;         if (kt < c) load_tile();
;         f32x16 s;
; #pragma unroll
;         for (int i = 0; i < 16; ++i) s[i] = 0.f;
;         const u16* kp = Ks + (kh * 32 + r) * 200 + hi * 8;
;         {
;           bf16x8 kf[4];
; #pragma unroll
;           for (int i = 0; i < 4; ++i) kf[i] = *(const bf16x8*)(kp + i * 16);
; #pragma unroll
;           for (int ks = 0; ks < 12; ++ks) {
;             __builtin_amdgcn_sched_barrier(0);
;             s = MFMA(kf[ks & 3], qf[ks], s);
;             if (ks + 4 < 12) kf[ks & 3] = *(const bf16x8*)(kp + (ks + 4) * 16);
;           }
;           __builtin_amdgcn_sched_barrier(0);
;         }
;         bf16x8 vf0[4];
; #pragma unroll
;         for (int dt = 0; dt < 4; ++dt) {
;           const u16* vp = Vs + (dt * 32 + r) * 68 + kh * 32 + 4 * hi;
;           const u32x2 v0 = *(const u32x2*)vp, v1 = *(const u32x2*)(vp + 8);
;           const u32x4 vv = {v0[0], v0[1], v1[0], v1[1]};
;           vf0[dt] = __builtin_bit_cast(bf16x8, vv);
;         }
;         float mx = s[0];
; #pragma unroll
;         for (int i = 1; i < 16; ++i) mx = fmaxf(mx, s[i]);
;         mx = fmaxf(mx, __shfl_xor(mx, 32));
;         const float mn = fmaxf(m, mx);
;         const float alpha = __builtin_amdgcn_exp2f(m - mn);
;         const bool resc = __builtin_amdgcn_ballot_w64(mn > m) != 0ull;
;         m = mn;
;         float rsum = 0.f;
; #pragma unroll
;         for (int i = 0; i < 16; ++i) { s[i] = __builtin_amdgcn_exp2f(s[i] - mn); rsum += s[i]; }
;         l = l * alpha + rsum;
;         if (resc) {
; #pragma unroll
;           for (int dt = 0; dt < 4; ++dt)
; #pragma unroll
;             for (int i = 0; i < 16; ++i) O[dt][i] *= alpha;
;         }
.LBB0_640:
	v_add_u32_e32 v3, 0x6410, v219
	s_waitcnt lgkmcnt(0)
	s_barrier
	s_waitcnt vmcnt(9)
	ds_write_b128 v193, v[132:135] offset:16
	s_waitcnt vmcnt(8)
	ds_write_b128 v193, v[136:139] offset:80
	s_waitcnt vmcnt(7)
	ds_write_b128 v193, v[140:143] offset:144
	s_waitcnt vmcnt(6)
	ds_write_b128 v193, v[144:147] offset:208
	s_waitcnt vmcnt(5)
	ds_write_b128 v193, v[148:151] offset:272
	s_waitcnt vmcnt(4)
	ds_write_b128 v193, v[152:155] offset:336
	s_waitcnt vmcnt(3)
	ds_write2_b64 v3, v[156:157], v[158:159] offset1:1
	v_add_u32_e32 v3, 0x6430, v219
	s_waitcnt vmcnt(2)
	ds_write2_b64 v3, v[160:161], v[162:163] offset1:1
	v_add_u32_e32 v3, 0x6450, v219
	s_waitcnt vmcnt(1)
	ds_write2_b64 v3, v[164:165], v[166:167] offset1:1
	v_add_u32_e32 v3, 0x6470, v219
	s_cmp_ge_u32 s22, s6
	s_waitcnt vmcnt(0)
	ds_write2_b64 v3, v[168:169], v[170:171] offset1:1
	s_waitcnt lgkmcnt(0)
	s_barrier
	ds_read_b128 v[68:71], v225 offset:16
	ds_read_b128 v[172:175], v225 offset:48
	ds_read_b128 v[176:179], v225 offset:80
	ds_read_b128 v[180:183], v225 offset:112
	s_cbranch_scc1 .LBB0_642
	global_load_dwordx4 v[132:135], v[216:217], off
	global_load_dwordx4 v[136:139], v[216:217], off offset:64
	global_load_dwordx4 v[140:143], v[216:217], off offset:128
	global_load_dwordx4 v[144:147], v[216:217], off offset:192
	global_load_dwordx4 v[148:151], v[216:217], off offset:256
	global_load_dwordx4 v[152:155], v[216:217], off offset:320
	global_load_dwordx4 v[156:159], v[214:215], off
	global_load_dwordx4 v[160:163], v[214:215], off offset:32
	global_load_dwordx4 v[164:167], v[214:215], off offset:64
	global_load_dwordx4 v[168:171], v[214:215], off offset:96
	v_lshl_add_u64 v[216:217], v[216:217], 0, s[10:11]
	v_lshl_add_u64 v[214:215], v[214:215], 0, s[14:15]
.LBB0_642:
	s_waitcnt lgkmcnt(3)
	v_mfma_f32_32x32x16_bf16 v[68:83], v[68:71], v[84:87], 0
	ds_read_b128 v[184:187], v225 offset:144
	s_waitcnt lgkmcnt(3)
	v_mfma_f32_32x32x16_bf16 v[68:83], v[172:175], v[88:91], v[68:83]
	ds_read_b128 v[232:235], v225 offset:176
	s_waitcnt lgkmcnt(3)
	v_mfma_f32_32x32x16_bf16 v[68:83], v[176:179], v[92:95], v[68:83]
	ds_read_b128 v[172:175], v225 offset:208
	s_waitcnt lgkmcnt(3)
	v_mfma_f32_32x32x16_bf16 v[68:83], v[180:183], v[96:99], v[68:83]
	ds_read_b128 v[176:179], v225 offset:240
	s_waitcnt lgkmcnt(3)
	v_mfma_f32_32x32x16_bf16 v[68:83], v[184:187], v[100:103], v[68:83]
	ds_read_b128 v[180:183], v225 offset:272
	s_waitcnt lgkmcnt(3)
	v_mfma_f32_32x32x16_bf16 v[68:83], v[232:235], v[104:107], v[68:83]
	ds_read_b128 v[184:187], v225 offset:304
	s_waitcnt lgkmcnt(3)
	v_mfma_f32_32x32x16_bf16 v[68:83], v[172:175], v[108:111], v[68:83]
	ds_read_b128 v[232:235], v225 offset:336
	s_waitcnt lgkmcnt(3)
	v_mfma_f32_32x32x16_bf16 v[68:83], v[176:179], v[112:115], v[68:83]
	ds_read_b128 v[172:175], v225 offset:368
	s_waitcnt lgkmcnt(3)
	v_mfma_f32_32x32x16_bf16 v[68:83], v[180:183], v[116:119], v[68:83]
	s_waitcnt lgkmcnt(2)
	v_mfma_f32_32x32x16_bf16 v[68:83], v[184:187], v[120:123], v[68:83]
	s_waitcnt lgkmcnt(1)
	v_mfma_f32_32x32x16_bf16 v[68:83], v[232:235], v[124:127], v[68:83]
	s_waitcnt lgkmcnt(0)
	v_mfma_f32_32x32x16_bf16 v[68:83], v[172:175], v[128:131], v[68:83]
	v_add_u32_e32 v3, 0x6000, v226
	ds_read2_b64 v[172:175], v3 offset0:130 offset1:132
	v_add_u32_e32 v3, 0x7000, v226
	ds_read2_b64 v[176:179], v3 offset0:162 offset1:164
	s_nop 7
	v_max_f32_e32 v3, v69, v69
	v_max_f32_e32 v180, v68, v68
	v_max_f32_e32 v3, v180, v3
	v_max3_f32 v3, v3, v70, v71
	v_max3_f32 v3, v3, v72, v73
	v_max3_f32 v3, v3, v74, v75
	v_max3_f32 v3, v3, v76, v77
	v_max3_f32 v3, v3, v78, v79
	v_max3_f32 v3, v3, v80, v81
	v_max3_f32 v3, v3, v82, v83
	v_mov_b32_e32 v218, v3
	v_mov_b32_e32 v180, v3
	v_add_u32_e32 v184, 0x8000, v226
	ds_read2_b64 v[184:187], v184 offset0:194 offset1:196
	v_permlane32_swap_b32_e32 v218, v180
	v_max_f32_e32 v218, v218, v180
	v_add_u32_e32 v180, 0x9000, v226
	ds_read2_b64 v[180:183], v180 offset0:226 offset1:228
	s_waitcnt lgkmcnt(2)
	v_max3_f32 v3, v231, v3, v218
	v_sub_f32_e32 v218, v231, v3
	v_exp_f32_e32 v218, v218
	v_cmp_gt_f32_e32 vcc, v3, v231
	s_cbranch_vccz .LBB0_644
	v_pk_mul_f32 v[66:67], v[66:67], v[218:219] op_sel_hi:[1,0]
	v_pk_mul_f32 v[64:65], v[64:65], v[218:219] op_sel_hi:[1,0]
	v_pk_mul_f32 v[62:63], v[62:63], v[218:219] op_sel_hi:[1,0]
	v_pk_mul_f32 v[60:61], v[60:61], v[218:219] op_sel_hi:[1,0]
	v_pk_mul_f32 v[58:59], v[58:59], v[218:219] op_sel_hi:[1,0]
	v_pk_mul_f32 v[56:57], v[56:57], v[218:219] op_sel_hi:[1,0]
	v_pk_mul_f32 v[54:55], v[54:55], v[218:219] op_sel_hi:[1,0]
	v_pk_mul_f32 v[52:53], v[52:53], v[218:219] op_sel_hi:[1,0]
	v_pk_mul_f32 v[50:51], v[50:51], v[218:219] op_sel_hi:[1,0]
	v_pk_mul_f32 v[48:49], v[48:49], v[218:219] op_sel_hi:[1,0]
	v_pk_mul_f32 v[46:47], v[46:47], v[218:219] op_sel_hi:[1,0]
	v_pk_mul_f32 v[44:45], v[44:45], v[218:219] op_sel_hi:[1,0]
	v_pk_mul_f32 v[42:43], v[42:43], v[218:219] op_sel_hi:[1,0]
	v_pk_mul_f32 v[40:41], v[40:41], v[218:219] op_sel_hi:[1,0]
	v_pk_mul_f32 v[38:39], v[38:39], v[218:219] op_sel_hi:[1,0]
	v_pk_mul_f32 v[36:37], v[36:37], v[218:219] op_sel_hi:[1,0]
	v_pk_mul_f32 v[34:35], v[34:35], v[218:219] op_sel_hi:[1,0]
	v_pk_mul_f32 v[32:33], v[32:33], v[218:219] op_sel_hi:[1,0]
	v_pk_mul_f32 v[30:31], v[30:31], v[218:219] op_sel_hi:[1,0]
	v_pk_mul_f32 v[28:29], v[28:29], v[218:219] op_sel_hi:[1,0]
	v_pk_mul_f32 v[26:27], v[26:27], v[218:219] op_sel_hi:[1,0]
	v_pk_mul_f32 v[24:25], v[24:25], v[218:219] op_sel_hi:[1,0]
	v_pk_mul_f32 v[22:23], v[22:23], v[218:219] op_sel_hi:[1,0]
	v_pk_mul_f32 v[20:21], v[20:21], v[218:219] op_sel_hi:[1,0]
	v_pk_mul_f32 v[18:19], v[18:19], v[218:219] op_sel_hi:[1,0]
	v_pk_mul_f32 v[16:17], v[16:17], v[218:219] op_sel_hi:[1,0]
	v_pk_mul_f32 v[14:15], v[14:15], v[218:219] op_sel_hi:[1,0]
	v_pk_mul_f32 v[12:13], v[12:13], v[218:219] op_sel_hi:[1,0]
	v_pk_mul_f32 v[10:11], v[10:11], v[218:219] op_sel_hi:[1,0]
	v_pk_mul_f32 v[8:9], v[8:9], v[218:219] op_sel_hi:[1,0]
	v_pk_mul_f32 v[6:7], v[6:7], v[218:219] op_sel_hi:[1,0]
	v_pk_mul_f32 v[4:5], v[4:5], v[218:219] op_sel_hi:[1,0]
; #define MFMA(a, b, c) __builtin_amdgcn_mfma_f32_32x32x16_bf16((a), (b), (c), 0, 0, 0)
; DI unsigned pk2(float a, float b) { f2_t v = {a, b}; bf2_t r = __builtin_convertvector(v, bf2_t); return __builtin_bit_cast(unsigned, r); }
; DI void phase4(const Params& p, char* smem) {
;     ...
;         float rsum = 0.f;
; #pragma unroll
;         for (int i = 0; i < 16; ++i) { s[i] = __builtin_amdgcn_exp2f(s[i] - mn); rsum += s[i]; }
;         l = l * alpha + rsum;
;         if (resc) {
; #pragma unroll
;           for (int dt = 0; dt < 4; ++dt)
; #pragma unroll
;             for (int i = 0; i < 16; ++i) O[dt][i] *= alpha;
;         }
;         {
;           const u32x4 pu0 = {pk2(s[0], s[1]), pk2(s[2], s[3]), pk2(s[4], s[5]), pk2(s[6], s[7])};
;           const u32x4 pu1 = {pk2(s[8], s[9]), pk2(s[10], s[11]), pk2(s[12], s[13]), pk2(s[14], s[15])};
;           const bf16x8 pf0 = __builtin_bit_cast(bf16x8, pu0), pf1 = __builtin_bit_cast(bf16x8, pu1);
;           bf16x8 vf1[4];
; #pragma unroll
;           for (int dt = 0; dt < 4; ++dt) {
;             const u16* vp = Vs + (dt * 32 + r) * 68 + kh * 32 + 16 + 4 * hi;
;             const u32x2 v0 = *(const u32x2*)vp, v1 = *(const u32x2*)(vp + 8);
;             const u32x4 vv = {v0[0], v0[1], v1[0], v1[1]};
;             vf1[dt] = __builtin_bit_cast(bf16x8, vv);
;           }
;           __builtin_amdgcn_sched_barrier(0);
; #pragma unroll
;           for (int dt = 0; dt < 4; ++dt) O[dt] = MFMA(vf0[dt], pf0, O[dt]);
; #pragma unroll
;           for (int dt = 0; dt < 4; ++dt) O[dt] = MFMA(vf1[dt], pf1, O[dt]);
.LBB0_644:
	v_sub_f32_e32 v68, v68, v3
	v_exp_f32_e32 v231, v68
	v_sub_f32_e32 v68, v69, v3
	v_exp_f32_e32 v69, v68
	v_sub_f32_e32 v68, v70, v3
	v_sub_f32_e32 v70, v72, v3
	v_exp_f32_e32 v232, v68
	v_sub_f32_e32 v68, v71, v3
	v_exp_f32_e32 v72, v70
	v_sub_f32_e32 v70, v73, v3
	v_exp_f32_e32 v71, v68
	v_exp_f32_e32 v73, v70
	v_sub_f32_e32 v70, v74, v3
	v_add_f32_e32 v68, 0, v231
	v_exp_f32_e32 v74, v70
	v_sub_f32_e32 v70, v75, v3
	v_add_f32_e32 v68, v69, v68
	v_exp_f32_e32 v75, v70
	v_add_f32_e32 v68, v232, v68
	v_add_f32_e32 v68, v71, v68
	v_add_f32_e32 v68, v72, v68
	v_add_f32_e32 v68, v73, v68
	v_add_f32_e32 v68, v74, v68
	v_add_f32_e32 v68, v75, v68
	v_cvt_pk_bf16_f32 v70, v231, v69
	v_cvt_pk_bf16_f32 v71, v232, v71
	v_cvt_pk_bf16_f32 v72, v72, v73
	v_cvt_pk_bf16_f32 v73, v74, v75
	s_nop 1
	v_mfma_f32_32x32x16_bf16 v[52:67], v[172:175], v[70:73], v[52:67]
	v_mfma_f32_32x32x16_bf16 v[36:51], v[176:179], v[70:73], v[36:51]
	s_waitcnt lgkmcnt(1)
	v_mfma_f32_32x32x16_bf16 v[20:35], v[184:187], v[70:73], v[20:35]
	s_waitcnt lgkmcnt(0)
	v_mfma_f32_32x32x16_bf16 v[4:19], v[180:183], v[70:73], v[4:19]
	v_sub_f32_e32 v231, v76, v3
	v_exp_f32_e32 v240, v231
	v_sub_f32_e32 v69, v77, v3
	v_exp_f32_e32 v241, v69
	v_add_f32_e32 v68, v240, v68
	v_sub_f32_e32 v231, v78, v3
	v_exp_f32_e32 v242, v231
	v_add_f32_e32 v68, v241, v68
	v_sub_f32_e32 v69, v79, v3
	v_exp_f32_e32 v243, v69
	v_add_f32_e32 v68, v242, v68
	v_sub_f32_e32 v231, v80, v3
	v_exp_f32_e32 v244, v231
	v_add_f32_e32 v68, v243, v68
	v_sub_f32_e32 v69, v81, v3
	v_exp_f32_e32 v245, v69
	v_add_f32_e32 v68, v244, v68
	v_add_u32_e32 v69, 0x6000, v227
	ds_read2_b64 v[74:77], v69 offset0:134 offset1:136
	v_add_u32_e32 v69, 0x7000, v227
	ds_read2_b64 v[78:81], v69 offset0:166 offset1:168
	v_add_u32_e32 v69, 0x8000, v227
	ds_read2_b64 v[232:235], v69 offset0:198 offset1:200
	v_add_u32_e32 v69, 0x9000, v227
	ds_read2_b64 v[236:239], v69 offset0:230 offset1:232
	v_sub_f32_e32 v231, v82, v3
	v_exp_f32_e32 v82, v231
	v_add_f32_e32 v68, v245, v68
	v_sub_f32_e32 v231, v83, v3
	v_exp_f32_e32 v83, v231
	v_add_f32_e32 v68, v82, v68
	v_add_f32_e32 v68, v83, v68
	v_fmac_f32_e32 v68, v201, v218
	v_cvt_pk_bf16_f32 v240, v240, v241
	v_cvt_pk_bf16_f32 v241, v242, v243
	v_cvt_pk_bf16_f32 v242, v244, v245
	v_cvt_pk_bf16_f32 v243, v82, v83
	s_add_i32 s22, s22, 1
	s_cmp_eq_u32 s7, s22
	s_waitcnt lgkmcnt(3)
	v_mfma_f32_32x32x16_bf16 v[52:67], v[74:77], v[240:243], v[52:67]
	s_waitcnt lgkmcnt(2)
	v_mfma_f32_32x32x16_bf16 v[36:51], v[78:81], v[240:243], v[36:51]
	s_waitcnt lgkmcnt(1)
	v_mfma_f32_32x32x16_bf16 v[20:35], v[232:235], v[240:243], v[20:35]
	s_waitcnt lgkmcnt(0)
	v_mfma_f32_32x32x16_bf16 v[4:19], v[236:239], v[240:243], v[4:19]
	s_cbranch_scc1 .LBB0_646
	v_mov_b32_e32 v201, v68
	v_mov_b32_e32 v231, v3
	s_branch .LBB0_640
